# per-head max q/k norms taken from the in-proj GEMM accumulators in its epilogue; separate norm pass over proj removed
# speedup vs baseline: 1.0024x; 1.0024x over previous
; __device__ __forceinline__ int get_tid() { int t = threadIdx.x; asm volatile("" : "+v"(t)); return t; }
; __device__ void attn_item(const Params& p, int s_idx, char* smem) {
;     const int qb = 63 - (s_idx >> 5), bh = s_idx & 31, b = bh >> 3, h = bh & 7;
;     const int tid = get_tid(), lane = tid & 63, wid = tid >> 6, ql = lane & 31, hh = lane >> 5;
;     const int qrow = qb * 128 + wid * 32 + ql;
;     const bf16_t* projb = p.proj + (size_t)b * S * NIN;
;     bf16x8 qf[4];
; #pragma unroll
;     for (int kk = 0; kk < 4; ++kk) qf[kk] = *(const bf16x8*)(projb + (size_t)qrow * NIN + h * 64 + kk * 16 + hh * 8);
;     f32x16 O0, O1;
; #pragma unroll
;     for (int i = 0; i < 16; ++i) { O0[i] = 0.f; O1[i] = 0.f; }
;     float mrun = -INFINITY, lsum = 0.f;
;     const int nkt = qb * 2 + 2;
;     const int wave_last = (qb * 128 + wid * 32 + 31) >> 6;
;     const int wave_q0 = qb * 128 + wid * 32;
;     const float sc = 0.125f * LOG2E;
;     struct KV { u32x4 rk[2], rv[2]; float rkb; };
;     KV sa;
;     auto gload = [&](int kt, KV& st) {
; #pragma unroll
;         for (int i = 0; i < 2; ++i) {
;             const int c = tid + 256 * i, key = c >> 3, dc = c & 7;
;             const bf16_t* src = projb + (size_t)(kt * 64 + key) * NIN + h * 64 + dc * 8;
;             st.rk[i] = *(const u32x4*)(src + 512);
;             const int keyv = c & 63, dcv = c >> 6;
;             st.rv[i] = *(const u32x4*)(projb + (size_t)(kt * 64 + keyv) * NIN + 1024 + h * 64 + dcv * 8);
;         }
;         st.rkb = p.kb[(size_t)bh * S + kt * 64 + (tid & 63)];
;     ...
;     gload(0, sa); sstore(0, sa); __syncthreads();
.LBB0_107:
	s_ashr_i32 s12, s15, 5
	s_lshl_b32 s13, s15, 10
	s_sub_i32 s14, 63, s12
	v_mov_b32_e32 v3, v126
	s_and_b32 s13, s13, 0x6000
	s_and_b32 s18, s15, 31
	s_lshl_b32 s12, s14, 7
	v_ashrrev_i32_e32 v143, 6, v3
	s_mul_i32 s16, s13, 0x1410
	v_lshlrev_b32_e32 v96, 5, v143
	s_add_u32 s34, s90, s16
	v_and_b32_e32 v2, 31, v3
	v_add_u32_e32 v144, s12, v96
	s_addc_u32 s35, s91, 0
	s_lshl_b32 s15, s15, 6
	v_or_b32_e32 v98, v144, v2
	s_waitcnt lgkmcnt(0)
	v_mov_b64_e32 v[0:1], s[34:35]
	s_and_b32 s15, s15, 0x1c0
	v_bfe_u32 v4, v3, 5, 1
	v_mad_i64_i32 v[6:7], s[16:17], v98, s29, v[0:1]
	s_lshl_b32 s22, s15, 1
	s_mov_b32 s23, s21
	v_lshl_add_u64 v[6:7], v[6:7], 0, s[22:23]
	v_lshlrev_b32_e32 v112, 4, v4
	v_lshl_add_u64 v[6:7], v[6:7], 0, v[112:113]
	v_ashrrev_i32_e32 v145, 3, v3
	v_lshlrev_b32_e32 v5, 3, v3
	global_load_dwordx4 v[64:67], v[6:7], off
	global_load_dwordx4 v[68:71], v[6:7], off offset:32
	global_load_dwordx4 v[72:75], v[6:7], off offset:64
	global_load_dwordx4 v[76:79], v[6:7], off offset:96
	v_readlane_b32 s98, v165, 2
	v_readlane_b32 s99, v165, 3
	v_readlane_b32 s32, v167, 36
	v_and_b32_e32 v32, 7, v130
	v_bfe_u32 v33, v130, 3, 1
	v_lshlrev_b32_e32 v32, 7, v32
	s_mul_i32 s32, s32, 0xc00
	v_lshl_or_b32 v32, v33, 10, v32
	v_mov_b32_e32 v33, s18
	s_add_i32 s32, s32, 32
	v_and_b32_e32 v33, 7, v33
	v_add_u32_e32 v32, s32, v32
	v_lshl_add_u32 v32, v33, 2, v32
	global_load_dword v34, v32, s[98:99] sc0 sc1
	s_lshl_b32 s32, s18, 15
	v_lshlrev_b32_e32 v35, 8, v130
	v_add_u32_e32 v35, s32, v35
	v_add_u32_e32 v38, 0x4000, v35
	s_lshl_b32 s32, s14, 9
	v_add_u32_e32 v39, s32, v35
	v_lshlrev_b32_e32 v33, 8, v130
	v_sub_u32_e32 v39, v39, v33
	v_readlane_b32 s98, v165, 40
	v_readlane_b32 s99, v165, 41
	s_nop 4
	s_nop 0
	global_load_dword v36, v35, s[98:99] offset:252
	global_load_dword v37, v38, s[98:99] offset:252
	global_load_dword v39, v39, s[98:99]
	s_waitcnt vmcnt(3)
	v_max_u32_dpp v34, v34, v34 quad_perm:[1,0,3,2] row_mask:0xf bank_mask:0xf
	s_nop 1
	v_max_u32_dpp v34, v34, v34 quad_perm:[2,3,0,1] row_mask:0xf bank_mask:0xf
	s_nop 1
	v_max_u32_dpp v34, v34, v34 row_half_mirror row_mask:0xf bank_mask:0xf
	s_waitcnt vmcnt(0)
	s_nop 0
	v_readlane_b32 s98, v34, 0
	v_readlane_b32 s99, v34, 8
	v_mov_b32_e32 v41, 0xbebae186
	s_nop 0
	v_mov_b32_e32 v40, s98
	v_mul_f32_e32 v40, s99, v40
	v_sqrt_f32_e32 v40, v40
	s_nop 0
	v_fma_f32 v40, v40, v41, v39
	v_add_f32_e32 v40, 0xc31b0000, v40
	v_cmp_lt_f32_e32 vcc, v36, v40
	s_bcnt1_i32_b64 s32, vcc
	v_cmp_lt_f32_e32 vcc, v37, v40
	s_bcnt1_i32_b64 s98, vcc
	s_add_i32 s32, s32, s98
	s_lshl_b32 s98, s14, 1
	s_min_i32 s32, s32, s98
	s_and_b32 s32, s32, -2
	s_lshl_b32 s98, s32, 6
	s_lshl_b32 s99, s14, 7
	s_add_i32 s99, s99, 64
	s_mul_i32 s99, s99, 0x1410
	s_add_u32 s34, s34, s99
	s_addc_u32 s35, s35, 0
	s_lshl_b32 s99, s14, 1
	s_add_i32 s99, s99, 1
	s_sub_i32 s99, s99, s32
	s_lshl_b32 s99, s99, 6
	v_subrev_u32_e32 v98, s98, v98
	v_subrev_u32_e32 v144, s98, v144
	v_mov_b64_e32 v[0:1], s[34:35]
	v_mad_i64_i32 v[6:7], s[16:17], v145, s29, v[0:1]
	v_and_b32_e32 v5, 56, v5
	v_lshl_add_u64 v[6:7], v[6:7], 0, s[22:23]
	v_lshlrev_b32_e32 v112, 1, v5
	v_lshl_add_u64 v[6:7], v[6:7], 0, v[112:113]
	global_load_dwordx4 v[6:9], v[6:7], off offset:1024
	v_add_u32_e32 v5, 0x100, v3
	v_and_b32_e32 v114, 63, v3
	v_ashrrev_i32_e32 v146, 3, v5
	v_mul_u32_u24_e32 v10, 0x1410, v114
	v_mov_b32_e32 v11, v113
	v_mad_i64_i32 v[0:1], s[16:17], v146, s29, v[0:1]
	v_readlane_b32 s48, v165, 26
	v_lshl_add_u64 v[10:11], s[34:35], 0, v[10:11]
	v_and_b32_e32 v100, -8, v145
	v_lshl_add_u64 v[0:1], v[0:1], 0, s[22:23]
	v_and_b32_e32 v102, -8, v146
	s_lshl_b32 s15, s18, 15
	v_readlane_b32 s62, v165, 40
	v_lshl_add_u64 v[14:15], v[10:11], 0, s[22:23]
	v_ashrrev_i32_e32 v101, 31, v100
	v_lshl_add_u64 v[0:1], v[0:1], 0, v[112:113]
	v_ashrrev_i32_e32 v103, 31, v102
	v_readlane_b32 s63, v165, 41
	s_add_u32 s16, s62, s15
	v_lshl_add_u64 v[16:17], v[100:101], 1, v[14:15]
	global_load_dwordx4 v[10:13], v[0:1], off offset:1024
	v_lshl_add_u64 v[0:1], v[102:103], 1, v[14:15]
	s_addc_u32 s17, s63, 0
	s_lshl_b32 s98, s98, 2
	s_add_u32 s16, s16, s98
	s_addc_u32 s17, s17, 0
	v_lshlrev_b32_e32 v14, 2, v114
	v_mov_b32_e32 v15, v113
	s_movk_i32 s15, 0x90
	v_lshl_add_u64 v[104:105], s[16:17], 0, v[14:15]
	v_mad_u64_u32 v[106:107], s[16:17], v145, s15, v[112:113]
	v_mul_lo_u32 v5, v100, s15
	v_lshlrev_b32_e32 v14, 1, v114
	v_or_b32_e32 v107, v5, v14
	v_mad_u64_u32 v[108:109], s[16:17], v146, s15, v[112:113]
	v_mul_lo_u32 v5, v102, s15
	s_movk_i32 s44, 0x90
	v_or_b32_e32 v109, v5, v14
	v_cmp_gt_i32_e64 s[40:41], 64, v3
	v_lshlrev_b32_e32 v147, 2, v3
	v_readlane_b32 s49, v165, 27
	v_readlane_b32 s50, v165, 28
	v_readlane_b32 s51, v165, 29
	v_readlane_b32 s52, v165, 30
	v_readlane_b32 s53, v165, 31
	v_readlane_b32 s54, v165, 32
	v_readlane_b32 s55, v165, 33
	v_readlane_b32 s56, v165, 34
	v_readlane_b32 s57, v165, 35
	v_readlane_b32 s58, v165, 36
	v_readlane_b32 s59, v165, 37
	v_readlane_b32 s60, v165, 38
	v_readlane_b32 s61, v165, 39
	s_waitcnt vmcnt(1)
	ds_write_b128 v106, v[6:9]
	global_load_dwordx4 v[6:9], v[16:17], off offset:2048
	s_waitcnt vmcnt(0)
	ds_write_b16 v107, v6 offset:9216
	ds_write_b16_d16_hi v107, v6 offset:9360
	ds_write_b16 v107, v7 offset:9504
	ds_write_b16_d16_hi v107, v7 offset:9648
	ds_write_b16 v107, v8 offset:9792
	ds_write_b16_d16_hi v107, v8 offset:9936
	ds_write_b16 v107, v9 offset:10080
	ds_write_b16_d16_hi v107, v9 offset:10224
	global_load_dwordx4 v[6:9], v[0:1], off offset:2048
	ds_write_b128 v108, v[10:13]
	s_waitcnt vmcnt(0)
	ds_write_b16 v109, v6 offset:9216
	ds_write_b16_d16_hi v109, v6 offset:9360
	ds_write_b16 v109, v7 offset:9504
	ds_write_b16_d16_hi v109, v7 offset:9648
	ds_write_b16 v109, v8 offset:9792
	ds_write_b16_d16_hi v109, v8 offset:9936
	ds_write_b16 v109, v9 offset:10080
	ds_write_b16_d16_hi v109, v9 offset:10224
	s_and_saveexec_b64 s[24:25], s[40:41]
	s_cbranch_execz .LBB0_109
	v_mov_b32_e32 v0, s99
	v_lshlrev_b32_e32 v0, 2, v0
	v_mov_b32_e32 v1, 0
	v_lshl_add_u64 v[0:1], v[104:105], 0, v[0:1]
	global_load_dword v0, v[0:1], off
	s_waitcnt vmcnt(0)
	ds_write_b32 v147, v0 offset:18432

; template <class Epi>
; __device__ __forceinline__ void gemm_tile64(const bf16_t* A, const bf16_t* Bt, int tm, int tn, const Epi& epi, char* smem, const float* ssq, int nparts) {
;     ...
;     auto compute = [&]() {
; #pragma unroll
;         for (int ks = 0; ks < 2; ++ks) {
;             bf16x8 af[4], bfr[4];
; #pragma unroll
;             for (int m = 0; m < 4; ++m) { const int r = wr * 64 + m * 16 + fr; af[m] = *(const bf16x8*)(sA + r * 64 + (((ks * 4 + fq) ^ ((r >> 1) & 7)) * 8)); }
; #pragma unroll
;             for (int n = 0; n < 4; ++n) { const int r = wc * 64 + n * 16 + fr; bfr[n] = *(const bf16x8*)(sB + r * 64 + (((ks * 4 + fq) ^ ((r >> 1) & 7)) * 8)); }
; #pragma unroll
;             for (int m = 0; m < 4; ++m)
; #pragma unroll
;                 for (int n = 0; n < 4; ++n) acc[m][n] = __builtin_amdgcn_mfma_f32_16x16x32_bf16(bfr[n], af[m], acc[m][n], 0, 0, 0);
;         }
;     __device__ __forceinline__ void operator()(const f32x4 (&acc)[4][4], int tm, int tn, int wr, int wc, int fr, int fq, const float* sRs) const {
;         const int col0 = tn * 128 + wc * 64 + fq * 16;
; #pragma unroll
;         for (int m = 0; m < 4; ++m) {
;             const int rl = wr * 64 + m * 16 + fr; const float rs = sRs[rl]; const size_t row = (size_t)tm * 128 + rl;
;             const f32x4 v0 = acc[m][0] * rs, v1 = acc[m][1] * rs, v2 = acc[m][2] * rs, v3 = acc[m][3] * rs;
.Lgi_nopf:
	s_waitcnt lgkmcnt(3)
	v_mfma_f32_16x16x32_bf16 v[60:63], v[80:83], v[88:91], v[60:63]
	v_mfma_f32_16x16x32_bf16 v[56:59], v[84:87], v[88:91], v[56:59]
	s_waitcnt lgkmcnt(1)
	v_mfma_f32_16x16x32_bf16 v[52:55], v[116:119], v[88:91], v[52:55]
	s_waitcnt lgkmcnt(0)
	v_mfma_f32_16x16x32_bf16 v[48:51], v[120:123], v[88:91], v[48:51]
	v_mfma_f32_16x16x32_bf16 v[44:47], v[80:83], v[92:95], v[44:47]
	v_mfma_f32_16x16x32_bf16 v[40:43], v[84:87], v[92:95], v[40:43]
	v_mfma_f32_16x16x32_bf16 v[36:39], v[116:119], v[92:95], v[36:39]
	v_mfma_f32_16x16x32_bf16 v[32:35], v[120:123], v[92:95], v[32:35]
	ds_read_b128 v[88:91], v108 offset:4096
	ds_read_b128 v[92:95], v108 offset:6144
	s_waitcnt lgkmcnt(1)
	v_mfma_f32_16x16x32_bf16 v[28:31], v[80:83], v[88:91], v[28:31]
	v_mfma_f32_16x16x32_bf16 v[24:27], v[84:87], v[88:91], v[24:27]
	v_mfma_f32_16x16x32_bf16 v[16:19], v[116:119], v[88:91], v[16:19]
	v_mfma_f32_16x16x32_bf16 v[12:15], v[120:123], v[88:91], v[12:15]
	s_waitcnt lgkmcnt(0)
	v_mfma_f32_16x16x32_bf16 v[8:11], v[80:83], v[92:95], v[8:11]
	v_mfma_f32_16x16x32_bf16 v[20:23], v[84:87], v[92:95], v[20:23]
	ds_read_b128 v[80:83], v111 offset:16384
	ds_read_b128 v[84:87], v111 offset:18432
	v_mfma_f32_16x16x32_bf16 v[4:7], v[116:119], v[92:95], v[4:7]
	v_mfma_f32_16x16x32_bf16 v[0:3], v[120:123], v[92:95], v[0:3]
	ds_read_b128 v[88:91], v110
	ds_read_b128 v[92:95], v110 offset:2048
	ds_read_b128 v[116:119], v111 offset:20480
	ds_read_b128 v[120:123], v111 offset:22528
	s_waitcnt lgkmcnt(3)
	v_mfma_f32_16x16x32_bf16 v[60:63], v[80:83], v[88:91], v[60:63]
	v_mfma_f32_16x16x32_bf16 v[56:59], v[84:87], v[88:91], v[56:59]
	s_waitcnt lgkmcnt(1)
	v_mfma_f32_16x16x32_bf16 v[52:55], v[116:119], v[88:91], v[52:55]
	s_waitcnt lgkmcnt(0)
	v_mfma_f32_16x16x32_bf16 v[48:51], v[120:123], v[88:91], v[48:51]
	ds_read_b128 v[88:91], v110 offset:4096
	ds_read_b128 v[144:147], v110 offset:6144
	v_mfma_f32_16x16x32_bf16 v[44:47], v[80:83], v[92:95], v[44:47]
	v_mfma_f32_16x16x32_bf16 v[40:43], v[84:87], v[92:95], v[40:43]
	v_mfma_f32_16x16x32_bf16 v[36:39], v[116:119], v[92:95], v[36:39]
	v_mfma_f32_16x16x32_bf16 v[32:35], v[120:123], v[92:95], v[32:35]
	s_waitcnt lgkmcnt(1)
	v_mfma_f32_16x16x32_bf16 v[28:31], v[80:83], v[88:91], v[28:31]
	v_mfma_f32_16x16x32_bf16 v[24:27], v[84:87], v[88:91], v[24:27]
	v_mfma_f32_16x16x32_bf16 v[16:19], v[116:119], v[88:91], v[16:19]
	v_mfma_f32_16x16x32_bf16 v[12:15], v[120:123], v[88:91], v[12:15]
	s_waitcnt lgkmcnt(0)
	v_mfma_f32_16x16x32_bf16 v[8:11], v[80:83], v[144:147], v[8:11]
	v_mfma_f32_16x16x32_bf16 v[20:23], v[84:87], v[144:147], v[20:23]
	v_mfma_f32_16x16x32_bf16 v[4:7], v[116:119], v[144:147], v[4:7]
	v_mfma_f32_16x16x32_bf16 v[0:3], v[120:123], v[144:147], v[0:3]
	s_cmp_eq_u32 s0, 17
	s_cbranch_scc0 .LBB0_376
	s_mov_b32 s21, 0
	s_movk_i32 s20, 0x780
	s_mov_b32 s1, 15
	s_cmp_lt_u32 s22, 8
	s_cbranch_scc0 .Lnq_skip
	v_mul_f32_e32 v64, v48, v48
	v_fmac_f32_e32 v64, v49, v49
	v_fmac_f32_e32 v64, v50, v50
	v_fmac_f32_e32 v64, v51, v51
	v_fmac_f32_e32 v64, v52, v52
	v_fmac_f32_e32 v64, v53, v53
	v_fmac_f32_e32 v64, v54, v54
	v_fmac_f32_e32 v64, v55, v55
	v_fmac_f32_e32 v64, v56, v56
	v_fmac_f32_e32 v64, v57, v57
	v_fmac_f32_e32 v64, v58, v58
	v_fmac_f32_e32 v64, v59, v59
	v_fmac_f32_e32 v64, v60, v60
	v_fmac_f32_e32 v64, v61, v61
	v_fmac_f32_e32 v64, v62, v62
	v_fmac_f32_e32 v64, v63, v63
	v_mul_f32_e32 v65, v32, v32
	v_fmac_f32_e32 v65, v33, v33
	v_fmac_f32_e32 v65, v34, v34
	v_fmac_f32_e32 v65, v35, v35
	v_fmac_f32_e32 v65, v36, v36
	v_fmac_f32_e32 v65, v37, v37
	v_fmac_f32_e32 v65, v38, v38
	v_fmac_f32_e32 v65, v39, v39
	v_fmac_f32_e32 v65, v40, v40
	v_fmac_f32_e32 v65, v41, v41
	v_fmac_f32_e32 v65, v42, v42
	v_fmac_f32_e32 v65, v43, v43
	v_fmac_f32_e32 v65, v44, v44
	v_fmac_f32_e32 v65, v45, v45
	v_fmac_f32_e32 v65, v46, v46
	v_fmac_f32_e32 v65, v47, v47
	v_mul_f32_e32 v66, v12, v12
	v_fmac_f32_e32 v66, v13, v13
	v_fmac_f32_e32 v66, v14, v14
	v_fmac_f32_e32 v66, v15, v15
	v_fmac_f32_e32 v66, v16, v16
	v_fmac_f32_e32 v66, v17, v17
	v_fmac_f32_e32 v66, v18, v18
	v_fmac_f32_e32 v66, v19, v19
	v_fmac_f32_e32 v66, v24, v24
	v_fmac_f32_e32 v66, v25, v25
	v_fmac_f32_e32 v66, v26, v26
	v_fmac_f32_e32 v66, v27, v27
	v_fmac_f32_e32 v66, v28, v28
	v_fmac_f32_e32 v66, v29, v29
	v_fmac_f32_e32 v66, v30, v30
	v_fmac_f32_e32 v66, v31, v31
	v_mul_f32_e32 v67, v0, v0
	v_fmac_f32_e32 v67, v1, v1
	v_fmac_f32_e32 v67, v2, v2
	v_fmac_f32_e32 v67, v3, v3
	v_fmac_f32_e32 v67, v4, v4
	v_fmac_f32_e32 v67, v5, v5
	v_fmac_f32_e32 v67, v6, v6
	v_fmac_f32_e32 v67, v7, v7
	v_fmac_f32_e32 v67, v8, v8
	v_fmac_f32_e32 v67, v9, v9
	v_fmac_f32_e32 v67, v10, v10
	v_fmac_f32_e32 v67, v11, v11
	v_fmac_f32_e32 v67, v20, v20
	v_fmac_f32_e32 v67, v21, v21
	v_fmac_f32_e32 v67, v22, v22
	v_fmac_f32_e32 v67, v23, v23
	v_mov_b32_e32 v68, v64
	s_nop 1
	v_permlane16_swap_b32_e32 v68, v64
	v_add_f32_e32 v64, v64, v68
	v_mov_b32_e32 v68, v64
	s_nop 1
	v_permlane32_swap_b32_e32 v68, v64
	v_add_f32_e32 v64, v64, v68
	v_mov_b32_e32 v68, v65
	s_nop 1
	v_permlane16_swap_b32_e32 v68, v65
	v_add_f32_e32 v65, v65, v68
	v_mov_b32_e32 v68, v65
	s_nop 1
	v_permlane32_swap_b32_e32 v68, v65
	v_add_f32_e32 v65, v65, v68
	v_mov_b32_e32 v68, v66
	s_nop 1
	v_permlane16_swap_b32_e32 v68, v66
	v_add_f32_e32 v66, v66, v68
	v_mov_b32_e32 v68, v66
	s_nop 1
	v_permlane32_swap_b32_e32 v68, v66
	v_add_f32_e32 v66, v66, v68
	v_mov_b32_e32 v68, v67
	s_nop 1
	v_permlane16_swap_b32_e32 v68, v67
	v_add_f32_e32 v67, v67, v68
	v_mov_b32_e32 v68, v67
	s_nop 1
	v_permlane32_swap_b32_e32 v68, v67
	v_add_f32_e32 v67, v67, v68
	v_lshl_or_b32 v69, v96, 6, v98
	v_lshlrev_b32_e32 v69, 2, v69
	ds_read_b32 v70, v69 offset:32768
	ds_read_b32 v71, v69 offset:32832
	ds_read_b32 v72, v69 offset:32896
	ds_read_b32 v73, v69 offset:32960
	v_readlane_b32 s98, v165, 2
	v_readlane_b32 s99, v165, 3
	v_readlane_b32 s32, v167, 36
	s_waitcnt lgkmcnt(0)
	v_mul_f32_e32 v70, v70, v70
	v_mul_f32_e32 v64, v64, v70
	v_mul_f32_e32 v71, v71, v71
	v_mul_f32_e32 v65, v65, v71
	v_mul_f32_e32 v72, v72, v72
	v_mul_f32_e32 v66, v66, v72
	v_mul_f32_e32 v73, v73, v73
	v_mul_f32_e32 v67, v67, v73
	v_max3_f32 v64, v64, v65, v66
	v_max_f32_e32 v64, v64, v67
	s_mul_i32 s32, s32, 0xc00
	s_add_i32 s32, s32, 32
	v_mov_b32_e32 v69, s32
	s_and_b32 s32, s2, 7
	v_lshl_add_u32 v69, s32, 7, v69
	v_max_f32_dpp v64, v64, v64 row_ror:8 row_mask:0xf bank_mask:0xf
	s_lshr_b32 s32, s22, 2
	v_lshl_add_u32 v69, s32, 10, v69
	v_max_f32_dpp v64, v64, v64 row_ror:4 row_mask:0xf bank_mask:0xf
	s_and_b32 s32, s22, 3
	v_lshl_add_u32 v69, s32, 3, v69
	v_max_f32_dpp v64, v64, v64 quad_perm:[2,3,0,1] row_mask:0xf bank_mask:0xf
	v_lshl_add_u32 v69, v97, 2, v69
	v_cmp_eq_u32_e32 vcc, 0, v130
	v_max_f32_dpp v64, v64, v64 quad_perm:[1,0,3,2] row_mask:0xf bank_mask:0xf
	s_and_saveexec_b64 s[36:37], vcc
	global_atomic_umax v69, v64, s[98:99]
	s_or_b64 exec, exec, s[36:37]
; __device__ __forceinline__ float log1p_pos(float x) { return x < 0.0625f ? x * (1.0f - x * (0.5f - x * (0.33333334f - x * (0.25f - x * 0.2f)))) : __logf(1.0f + x); }
;     __device__ __forceinline__ void operator()(const f32x4 (&acc)[4][4], int tm, int tn, int wr, int wc, int fr, int fq, const float* sRs) const {
;         const int col0 = tn * 128 + wc * 64 + fq * 16;
; #pragma unroll
;         for (int m = 0; m < 4; ++m) {
;             const int rl = wr * 64 + m * 16 + fr; const float rs = sRs[rl]; const size_t row = (size_t)tm * 128 + rl;
;             const f32x4 v0 = acc[m][0] * rs, v1 = acc[m][1] * rs, v2 = acc[m][2] * rs, v3 = acc[m][3] * rs;
;             if (col0 == F0) {
;                 const float* bf = p->b_forget + l * 8;
;                 f32x4 o0, o1;
; #pragma unroll
;                 for (int j = 0; j < 4; ++j) {
;                     const float z0 = v0[j] + bf[j], z1 = v1[j] + bf[4 + j];
;                     o0[j] = fminf(z0, 0.f) - log1p_pos(__expf(-fabsf(z0))); o1[j] = fminf(z1, 0.f) - log1p_pos(__expf(-fabsf(z1)));
.Lnq_skip:
	v_lshl_or_b32 v66, v96, 6, v98
	v_lshlrev_b32_e32 v72, 2, v66
	ds_read_b32 v70, v72 offset:32768
	s_lshl_b32 s0, s22, 7
	v_lshlrev_b32_e32 v64, 6, v97
	v_lshlrev_b32_e32 v65, 4, v99
	v_or3_b32 v64, v64, s0, v65
	s_lshl_b64 s[36:37], s[46:47], 7
	s_movk_i32 s0, 0x600
	v_ashrrev_i32_e32 v67, 31, v66
	v_cmp_eq_u32_e32 vcc, s0, v64
	v_lshl_add_u64 v[68:69], s[36:37], 0, v[66:67]
	s_waitcnt lgkmcnt(0)
	v_pk_mul_f32 v[62:63], v[62:63], v[70:71] op_sel_hi:[1,0]
	v_pk_mul_f32 v[60:61], v[60:61], v[70:71] op_sel_hi:[1,0]
	v_pk_mul_f32 v[58:59], v[58:59], v[70:71] op_sel_hi:[1,0]
	v_pk_mul_f32 v[56:57], v[56:57], v[70:71] op_sel_hi:[1,0]
	s_and_saveexec_b64 s[40:41], vcc
	s_cbranch_execz .LBB0_411
	global_load_dword v65, v113, s[44:45]
	global_load_dword v71, v113, s[44:45] offset:16
	s_waitcnt vmcnt(1)
	v_add_f32_e32 v65, v60, v65
	v_mul_f32_e64 v67, |v65|, s94
	v_exp_f32_e32 v73, v67
	s_nop 0
	v_cmp_ngt_f32_e64 s[0:1], s96, v73
	s_and_saveexec_b64 s[12:13], s[0:1]
	s_xor_b64 s[42:43], exec, s[12:13]
	s_cbranch_execz .LBB0_380
	v_add_f32_e32 v67, 1.0, v73
	v_cmp_gt_f32_e64 s[0:1], s7, v67
	s_mov_b32 s8, 0x3f317217
	s_nop 0
	v_cndmask_b32_e64 v73, 0, 32, s[0:1]
	v_ldexp_f32 v67, v67, v73
	v_log_f32_e32 v67, v67
	s_nop 0
	v_mul_f32_e32 v73, 0x3f317217, v67
	v_fma_f32 v73, v67, s8, -v73
	v_fmac_f32_e32 v73, 0x3377d1cf, v67
	s_mov_b32 s8, 0x7f800000
	v_fmac_f32_e32 v73, 0x3f317217, v67
	v_cmp_lt_f32_e64 s[38:39], |v67|, s8
	s_nop 1
	v_cndmask_b32_e64 v67, v67, v73, s[38:39]
	v_cndmask_b32_e64 v73, 0, v140, s[0:1]
	v_sub_f32_e32 v67, v67, v73
